# res1 epilogue second touch-prefetch batch rows 5-7 (+6 on next counted wait); res2 epilogue vmcnt(5)->(7); plus previous edits
# baseline (speedup 1.0000x reference)
; #define GAS __attribute__((address_space(1)))
;     __device__ __forceinline__ const float* resrow(int row, int colb) const { return (row < 8192 ? res0 + (size_t)row * DM : res1 + (size_t)(row - 8192) * DM) + colb; }
;     __device__ __forceinline__ void operator()(f32x4 (&acc)[2][2][4][2], const Unit& u, int wr, int wc, int fr, int fq) const {
;     ...
;         { const int lane = fr + 16 * fq, cL = u.pn * BM + wc * 32 + (lane < 32 ? lane : 96 + lane);
;           float vg = 0.f, vb = 0.f, vt = 0.f;
;           if (hasln) { vg = *(const GAS float*)(pg + cL); vb = *(const GAS float*)(pb + cL); }
;           if (haszh) vt = *(const GAS float*)(tg + cL);
;           const float* rp = resrow(row0, colb);
; #pragma unroll
;           for (int bj = 0; bj < 2; ++bj) { rn[bj][0] = ldg4(rp + bj * HALF); rn[bj][1] = ldg4(rp + bj * HALF + 4); }
;           if (hasln) stn = ldg2(pstats + 2 * (size_t)row0);
;           asm volatile("" : "+v"(vg), "+v"(vb), "+v"(vt), "+v"(rn[0][0]), "+v"(rn[0][1]), "+v"(rn[1][0]), "+v"(rn[1][1]), "+v"(stn));
;     ...
;                 if (ai * 4 + m < 7) { const int rown = row0 + ((ai * 4 + m + 1) >> 2) * HALF + ((ai * 4 + m + 1) & 3) * 16; const float* rp = resrow(rown, colb);
; #pragma unroll
;                     for (int bj = 0; bj < 2; ++bj) { rn[bj][0] = ldg4(rp + bj * HALF); rn[bj][1] = ldg4(rp + bj * HALF + 4); }
;                     if (hasln) stn = ldg2(pstats + 2 * (size_t)rown);
;                 }
.LBB0_515:
	v_lshl_add_u32 v188, s82, 8, v1
	v_lshl_add_u64 v[122:123], v[122:123], 2, s[20:21]
	global_load_dword v122, v[122:123], off
	v_add_u32_e32 v123, 0xffffe000, v188
	v_cmp_gt_i32_e32 vcc, s55, v188
	v_ashrrev_i32_e32 v189, 31, v188
	v_mov_b32_e32 v128, s19
	v_cndmask_b32_e32 v126, v123, v188, vcc
	v_mov_b32_e32 v123, s5
	v_cndmask_b32_e32 v127, 0, v189, vcc
	v_cndmask_b32_e32 v129, v123, v128, vcc
	v_mov_b32_e32 v123, s95
	v_mov_b32_e32 v128, s4
	v_or_b32_e32 v190, s15, v204
	v_cndmask_b32_e32 v128, v123, v128, vcc
	v_lshlrev_b64 v[126:127], 13, v[126:127]
	v_lshl_add_u64 v[126:127], v[128:129], 0, v[126:127]
	v_ashrrev_i32_e32 v191, 31, v190
	v_lshl_add_u64 v[126:127], v[190:191], 2, v[126:127]
	global_load_dwordx4 v[154:157], v[126:127], off offset:16
	global_load_dwordx4 v[158:161], v[126:127], off
	global_load_dwordx4 v[146:149], v[126:127], off offset:528
	global_load_dwordx4 v[150:153], v[126:127], off offset:512
	v_mov_b32_e32 v242, v126
	v_mov_b32_e32 v243, v127
	v_add_co_u32_e32 v212, vcc, 0x40000, v126
	s_nop 1
	v_addc_co_u32_e32 v213, vcc, 0, v127, vcc
	global_load_dword v214, v[212:213], off
	global_load_dword v214, v[212:213], off offset:512
	v_add_co_u32_e32 v212, vcc, 0x60000, v126
	s_nop 1
	v_addc_co_u32_e32 v213, vcc, 0, v127, vcc
	global_load_dword v214, v[212:213], off
	global_load_dword v214, v[212:213], off offset:512
	v_add_co_u32_e32 v212, vcc, 0x100000, v126
	s_nop 1
	v_addc_co_u32_e32 v213, vcc, 0, v127, vcc
	global_load_dword v214, v[212:213], off
	global_load_dword v214, v[212:213], off offset:512
	s_and_b64 vcc, exec, s[12:13]
	v_mov_b32_e32 v197, 0
	s_cbranch_vccnz .LBB0_517
	v_lshl_add_u64 v[126:127], v[188:189], 3, s[26:27]
	global_load_dwordx2 v[196:197], v[126:127], off

;     __device__ __forceinline__ const float* resrow(int row, int colb) const { return (row < 8192 ? res0 + (size_t)row * DM : res1 + (size_t)(row - 8192) * DM) + colb; }
;     __device__ __forceinline__ void operator()(f32x4 (&acc)[2][2][4][2], const Unit& u, int wr, int wc, int fr, int fq) const {
;     ...
;                 if (ai * 4 + m < 7) { const int rown = row0 + ((ai * 4 + m + 1) >> 2) * HALF + ((ai * 4 + m + 1) & 3) * 16; const float* rp = resrow(rown, colb);
; #pragma unroll
;                     for (int bj = 0; bj < 2; ++bj) { rn[bj][0] = ldg4(rp + bj * HALF); rn[bj][1] = ldg4(rp + bj * HALF + 4); }
;                     if (hasln) stn = ldg2(pstats + 2 * (size_t)rown);
;                 }
;                 float* op = out + (size_t)row * DM + colb; h16* zp = zh + (size_t)row * DM + colb;
;                 float mu = 0.f, rs = 1.f; if (hasln) { mu = st.x * (1.0f / DM); rs = rsqrtf(fmaxf(st.y * (1.0f / DM) - mu * mu, 0.f) + LN_EPS); }
.LBB0_535:
	v_add_co_u32_e32 v244, vcc, 0x120000, v242
	s_nop 1
	v_addc_co_u32_e32 v245, vcc, 0, v243, vcc
	global_load_dword v246, v[244:245], off
	global_load_dword v246, v[244:245], off offset:512
	v_add_co_u32_e32 v244, vcc, 0x140000, v242
	s_nop 1
	v_addc_co_u32_e32 v245, vcc, 0, v243, vcc
	global_load_dword v246, v[244:245], off
	global_load_dword v246, v[244:245], off offset:512
	v_add_co_u32_e32 v244, vcc, 0x160000, v242
	s_nop 1
	v_addc_co_u32_e32 v245, vcc, 0, v243, vcc
	global_load_dword v246, v[244:245], off
	global_load_dword v246, v[244:245], off offset:512
	s_and_b64 vcc, exec, s[12:13]
	s_cbranch_vccnz .LBB0_537
	v_pk_mul_f32 v[138:139], v[148:149], s[54:55] op_sel_hi:[1,0]
	s_nop 0
	v_fma_f32 v126, -v138, v138, v139
	v_max_f32_e32 v126, 0, v126
	v_add_f32_e32 v126, 0x3727c5ac, v126
	v_mul_f32_e32 v127, 0x4b800000, v126
	v_cmp_gt_f32_e32 vcc, s60, v126
	s_nop 1
	v_cndmask_b32_e32 v126, v126, v127, vcc
	v_rsq_f32_e32 v126, v126
	s_nop 0
	v_mul_f32_e32 v127, 0x45800000, v126
	v_cndmask_b32_e32 v140, v126, v127, vcc
	s_and_b64 vcc, exec, s[12:13]
	v_mov_b32_e32 v141, v140
	s_cbranch_vccz .LBB0_538
	s_branch .LBB0_539

; #define LAS __attribute__((address_space(3)))
;     __device__ __forceinline__ void operator()(f32x4 (&acc)[2][2][4][2], const Unit& u, int wr, int wc, int fr, int fq) const {
;     ...
;                 if (ai * 4 + m < 7) { const int rown = row0 + ((ai * 4 + m + 1) >> 2) * HALF + ((ai * 4 + m + 1) & 3) * 16; const float* rp = resrow(rown, colb);
; #pragma unroll
;                     for (int bj = 0; bj < 2; ++bj) { rn[bj][0] = ldg4(rp + bj * HALF); rn[bj][1] = ldg4(rp + bj * HALF + 4); }
;                     if (hasln) stn = ldg2(pstats + 2 * (size_t)rown);
;                 }
;                 float* op = out + (size_t)row * DM + colb; h16* zp = zh + (size_t)row * DM + colb;
;                 float mu = 0.f, rs = 1.f; if (hasln) { mu = st.x * (1.0f / DM); rs = rsqrtf(fmaxf(st.y * (1.0f / DM) - mu * mu, 0.f) + LN_EPS); }
;                 float sm = 0.f, sq = 0.f;
; #pragma unroll
;                 for (int bj = 0; bj < 2; ++bj) {
;                     f32x4 r0 = r[bj][0], r1 = r[bj][1];
;                     if (hasln) { const f32x4 g0 = *(const LAS f32x4*)(slot + bj * 32 + 8 * fq), g1 = *(const LAS f32x4*)(slot + bj * 32 + 8 * fq + 4),
;                                              b0 = *(const LAS f32x4*)(slot + 64 + bj * 32 + 8 * fq), b1 = *(const LAS f32x4*)(slot + 64 + bj * 32 + 8 * fq + 4);
;                         r0 = (r0 - mu) * rs * g0 + b0; r1 = (r1 - mu) * rs * g1 + b1; }
;                     const f32x4 z0 = r0 * ALPHA + acc[ai][bj][m][0], z1 = r1 * ALPHA + acc[ai][bj][m][1];
;                     if (zf == nullptr) { stg4(op + bj * HALF, z0); stg4(op + bj * HALF + 4, z1); }
;                     else { u32x4 w; w.x = pk2(z0[0], z0[1]); w.y = pk2(z0[2], z0[3]); w.z = pk2(z1[0], z1[1]); w.w = pk2(z1[2], z1[3]); stg4h(zf + (size_t)row * DM + colb + bj * HALF, w); }
;                     sm += ((z0[0] + z0[1]) + (z0[2] + z0[3])) + ((z1[0] + z1[1]) + (z1[2] + z1[3]));
;                     sq += ((z0[0] * z0[0] + z0[1] * z0[1]) + (z0[2] * z0[2] + z0[3] * z0[3])) + ((z1[0] * z1[0] + z1[1] * z1[1]) + (z1[2] * z1[2] + z1[3] * z1[3]));
;                     if (haszh) {
;                         const f32x4 t0 = *(const LAS f32x4*)(slot + 128 + bj * 32 + 8 * fq), t1 = *(const LAS f32x4*)(slot + 128 + bj * 32 + 8 * fq + 4);
;                         const f32x4 y0 = z0 * t0, y1 = z1 * t1;
.LBB0_541:
	s_nop 0
	v_add_f32_e32 v130, v95, v94
	v_add_f32_e32 v131, v97, v96
	v_add_f32_e32 v130, v131, v130
	v_add_f32_e32 v131, v91, v90
	v_mul_f32_e32 v90, v90, v90
	v_fmac_f32_e32 v90, v91, v91
	v_mul_f32_e32 v91, v92, v92
	v_fmac_f32_e32 v91, v93, v93
	v_pk_fma_f32 v[88:89], v[120:121], s[94:95], v[88:89] op_sel_hi:[1,0,1]
	v_pk_fma_f32 v[86:87], v[118:119], s[94:95], v[86:87] op_sel_hi:[1,0,1]
	v_add_f32_e32 v132, v93, v92
	v_add_f32_e32 v90, v91, v90
	v_pk_fma_f32 v[84:85], v[116:117], s[94:95], v[84:85] op_sel_hi:[1,0,1]
	v_pk_fma_f32 v[82:83], v[114:115], s[94:95], v[82:83] op_sel_hi:[1,0,1]
	v_add_f32_e32 v91, v87, v86
	v_add_f32_e32 v92, v88, v89
	v_add_f32_e32 v131, v132, v131
	v_add_f32_e32 v91, v92, v91
	v_add_f32_e32 v92, v83, v82
	v_add_f32_e32 v93, v85, v84
	v_add_f32_e32 v130, v131, v130
	v_add_f32_e32 v92, v93, v92
	v_add_f32_e32 v130, 0, v130
	v_add_f32_e32 v91, v92, v91
	v_add_f32_e32 v114, v130, v91
	v_mul_f32_e32 v91, v86, v86
	v_mul_f32_e32 v92, v89, v89
	v_mul_f32_e32 v94, v94, v94
	v_fmac_f32_e32 v91, v87, v87
	v_fmac_f32_e32 v92, v88, v88
	v_fmac_f32_e32 v94, v95, v95
	v_mul_f32_e32 v95, v96, v96
	v_add_f32_e32 v91, v92, v91
	v_mul_f32_e32 v92, v82, v82
	v_mul_f32_e32 v93, v84, v84
	v_fmac_f32_e32 v95, v97, v97
	v_fmac_f32_e32 v92, v83, v83
	v_fmac_f32_e32 v93, v85, v85
	v_add_f32_e32 v94, v95, v94
	v_add_f32_e32 v92, v93, v92
	v_add_f32_e32 v90, v90, v94
	global_store_dwordx4 v[128:129], v[86:89], off offset:512
	global_store_dwordx4 v[128:129], v[82:85], off offset:528
	v_add_f32_e32 v91, v92, v91
	v_add_f32_e32 v115, v90, v91
	ds_read_b128 v[90:93], v209 offset:640
	ds_read_b128 v[94:97], v209 offset:656
	s_movk_i32 s15, 0x1f80
	v_cmp_gt_i32_e32 vcc, s15, v188
	s_waitcnt vmcnt(11)
	v_mov_b64_e32 v[116:117], v[124:125]
	s_waitcnt lgkmcnt(1)
	v_pk_mul_f32 v[88:89], v[88:89], v[92:93]
	v_pk_mul_f32 v[86:87], v[86:87], v[90:91]
	s_waitcnt lgkmcnt(0)
	v_pk_mul_f32 v[90:91], v[84:85], v[96:97]
	v_pk_mul_f32 v[84:85], v[82:83], v[94:95]
	v_cvt_pk_f16_f32 v82, v86, v87
	v_cvt_pk_f16_f32 v83, v88, v89
	v_cvt_pk_f16_f32 v84, v84, v85
	v_cvt_pk_f16_f32 v85, v90, v91
	global_store_dwordx4 v[126:127], v[82:85], off offset:256
	ds_bpermute_b32 v82, v159, v114
	v_mov_b32_e32 v86, s4
	v_mov_b32_e32 v84, s5
	v_mov_b32_e32 v85, s19
	v_cndmask_b32_e32 v85, v84, v85, vcc
	s_waitcnt lgkmcnt(0)
	v_add_f32_e32 v128, v114, v82
	ds_bpermute_b32 v82, v159, v115
	v_add_u32_e32 v114, 0x80, v188
	v_mov_b32_e32 v84, s95
	v_cndmask_b32_e32 v84, v84, v86, vcc
	s_waitcnt lgkmcnt(0)
	v_add_f32_e32 v130, v115, v82
	v_add_u32_e32 v82, 0xffffe080, v188
	v_ashrrev_i32_e32 v115, 31, v114
	v_cndmask_b32_e32 v83, 0, v115, vcc
	v_cndmask_b32_e32 v82, v82, v114, vcc
	v_lshlrev_b64 v[82:83], 13, v[82:83]
	v_lshl_add_u64 v[82:83], v[84:85], 0, v[82:83]
	v_lshl_add_u64 v[86:87], v[190:191], 2, v[82:83]
	global_load_dwordx4 v[90:93], v[86:87], off offset:16
	global_load_dwordx4 v[94:97], v[86:87], off
	global_load_dwordx4 v[82:85], v[86:87], off offset:528
	s_nop 0
	global_load_dwordx4 v[86:89], v[86:87], off offset:512
	ds_bpermute_b32 v129, v158, v128
	ds_bpermute_b32 v131, v158, v130
	s_and_b64 vcc, exec, s[12:13]
	s_cbranch_vccnz .LBB0_543
	v_lshl_add_u64 v[116:117], v[114:115], 3, s[26:27]
	global_load_dwordx2 v[116:117], v[116:117], off

; #define LAS __attribute__((address_space(3)))
;     __device__ __forceinline__ const float* resrow(int row, int colb) const { return (row < 8192 ? res0 + (size_t)row * DM : res1 + (size_t)(row - 8192) * DM) + colb; }
;     __device__ __forceinline__ void operator()(f32x4 (&acc)[2][2][4][2], const Unit& u, int wr, int wc, int fr, int fq) const {
;     ...
;                 if (ai * 4 + m < 7) { const int rown = row0 + ((ai * 4 + m + 1) >> 2) * HALF + ((ai * 4 + m + 1) & 3) * 16; const float* rp = resrow(rown, colb);
; #pragma unroll
;                     for (int bj = 0; bj < 2; ++bj) { rn[bj][0] = ldg4(rp + bj * HALF); rn[bj][1] = ldg4(rp + bj * HALF + 4); }
;                     if (hasln) stn = ldg2(pstats + 2 * (size_t)rown);
;                 }
;                 float* op = out + (size_t)row * DM + colb; h16* zp = zh + (size_t)row * DM + colb;
;                 float mu = 0.f, rs = 1.f; if (hasln) { mu = st.x * (1.0f / DM); rs = rsqrtf(fmaxf(st.y * (1.0f / DM) - mu * mu, 0.f) + LN_EPS); }
;                 float sm = 0.f, sq = 0.f;
; #pragma unroll
;                 for (int bj = 0; bj < 2; ++bj) {
;                     f32x4 r0 = r[bj][0], r1 = r[bj][1];
;                     if (hasln) { const f32x4 g0 = *(const LAS f32x4*)(slot + bj * 32 + 8 * fq), g1 = *(const LAS f32x4*)(slot + bj * 32 + 8 * fq + 4),
;                                              b0 = *(const LAS f32x4*)(slot + 64 + bj * 32 + 8 * fq), b1 = *(const LAS f32x4*)(slot + 64 + bj * 32 + 8 * fq + 4);
;                         r0 = (r0 - mu) * rs * g0 + b0; r1 = (r1 - mu) * rs * g1 + b1; }
;                     const f32x4 z0 = r0 * ALPHA + acc[ai][bj][m][0], z1 = r1 * ALPHA + acc[ai][bj][m][1];
;                     if (zf == nullptr) { stg4(op + bj * HALF, z0); stg4(op + bj * HALF + 4, z1); }
;                     else { u32x4 w; w.x = pk2(z0[0], z0[1]); w.y = pk2(z0[2], z0[3]); w.z = pk2(z1[0], z1[1]); w.w = pk2(z1[2], z1[3]); stg4h(zf + (size_t)row * DM + colb + bj * HALF, w); }
;                     sm += ((z0[0] + z0[1]) + (z0[2] + z0[3])) + ((z1[0] + z1[1]) + (z1[2] + z1[3]));
;                     sq += ((z0[0] * z0[0] + z0[1] * z0[1]) + (z0[2] * z0[2] + z0[3] * z0[3])) + ((z1[0] * z1[0] + z1[1] * z1[1]) + (z1[2] * z1[2] + z1[3] * z1[3]));
.LBB0_685:
	s_nop 1
	v_add_f32_e32 v114, v127, v126
	v_add_f32_e32 v115, v129, v128
	v_add_f32_e32 v114, v115, v114
	v_add_f32_e32 v115, v147, v146
	v_add_f32_e32 v116, v149, v148
	v_add_f32_e32 v115, v116, v115
	v_add_f32_e32 v114, v115, v114
	v_add_f32_e32 v164, 0, v114
	v_mul_f32_e32 v114, v126, v126
	v_mul_f32_e32 v115, v128, v128
	v_fmac_f32_e32 v114, v127, v127
	v_fmac_f32_e32 v115, v129, v129
	v_or_b32_e32 v190, 32, v184
	v_add_f32_e32 v165, v115, v114
	v_add_u32_e32 v114, 0xffffe020, v184
	v_ashrrev_i32_e32 v191, 31, v190
	v_cmp_gt_i32_e32 vcc, s55, v190
	v_mov_b32_e32 v116, s74
	v_mov_b32_e32 v117, s15
	v_cndmask_b32_e32 v115, 0, v191, vcc
	v_cndmask_b32_e32 v114, v114, v190, vcc
	v_cndmask_b32_e32 v117, v116, v117, vcc
	v_mov_b32_e32 v116, s71
	v_mov_b32_e32 v118, s14
	v_cndmask_b32_e32 v116, v116, v118, vcc
	v_lshlrev_b64 v[114:115], 13, v[114:115]
	v_lshl_add_u64 v[114:115], v[116:117], 0, v[114:115]
	v_lshl_add_u64 v[118:119], v[114:115], 0, v[188:189]
	global_load_dwordx4 v[122:125], v[118:119], off offset:16
	global_load_dwordx4 v[126:129], v[118:119], off
	global_load_dwordx4 v[114:117], v[118:119], off offset:528
	s_nop 0
	global_load_dwordx4 v[118:121], v[118:119], off offset:512
	v_lshl_add_u64 v[162:163], v[190:191], 3, s[36:37]
	global_load_dwordx2 v[194:195], v[162:163], off
	v_mul_f32_e32 v146, v146, v146
	v_fmac_f32_e32 v146, v147, v147
	v_mul_f32_e32 v147, v148, v148
	v_fmac_f32_e32 v147, v149, v149
	v_add_f32_e32 v146, v147, v146
	v_add_f32_e32 v147, v151, v150
	v_add_f32_e32 v148, v152, v153
	v_add_f32_e32 v147, v148, v147
	v_add_f32_e32 v148, v155, v154
	v_add_f32_e32 v149, v157, v156
	v_add_f32_e32 v148, v149, v148
	v_add_f32_e32 v147, v148, v147
	v_mul_f32_e32 v148, v150, v150
	v_mul_f32_e32 v149, v153, v153
	v_fmac_f32_e32 v148, v151, v151
	v_fmac_f32_e32 v149, v152, v152
	v_add_f32_e32 v148, v149, v148
	v_mul_f32_e32 v149, v154, v154
	v_mul_f32_e32 v150, v156, v156
	v_fmac_f32_e32 v149, v155, v155
	v_fmac_f32_e32 v150, v157, v157
	v_add_f32_e32 v149, v150, v149
	v_add_f32_e32 v146, v146, v165
	v_add_f32_e32 v148, v149, v148
	v_and_b32_e32 v149, 64, v221
	v_add_f32_e32 v148, v146, v148
	v_xor_b32_e32 v146, 16, v221
	v_add_u32_e32 v149, 64, v149
	v_cmp_lt_i32_e32 vcc, v146, v149
	v_add_f32_e32 v147, v164, v147
	v_xor_b32_e32 v150, 32, v221
	v_cndmask_b32_e32 v146, v221, v146, vcc
	v_lshlrev_b32_e32 v156, 2, v146
	ds_bpermute_b32 v146, v156, v147
	v_cmp_lt_i32_e32 vcc, v150, v149
	s_mov_b64 s[62:63], -1
	s_waitcnt lgkmcnt(0)
	v_add_f32_e32 v152, v147, v146
	s_waitcnt vmcnt(7)
	v_pk_mul_f32 v[146:147], v[196:197], s[54:55] op_sel_hi:[1,0]
	v_cndmask_b32_e32 v149, v221, v150, vcc
	v_fma_f32 v147, -v146, v146, v147
	v_max_f32_e32 v147, 0, v147
	v_add_f32_e32 v147, 0x3727c5ac, v147
	v_lshlrev_b32_e32 v157, 2, v149
	ds_bpermute_b32 v149, v156, v148
	v_mul_f32_e32 v150, 0x4b800000, v147
	v_cmp_gt_f32_e32 vcc, s60, v147
	ds_read_b128 v[162:165], v207
	ds_read_b128 v[170:173], v207 offset:16
	ds_read_b128 v[196:199], v207 offset:256
	ds_read_b128 v[210:213], v207 offset:272
	v_cndmask_b32_e32 v147, v147, v150, vcc
	v_rsq_f32_e32 v147, v147
	s_waitcnt lgkmcnt(4)
	v_add_f32_e32 v154, v148, v149
	ds_bpermute_b32 v153, v157, v152
	ds_bpermute_b32 v155, v157, v154
	v_mul_f32_e32 v148, 0x45800000, v147
	v_cndmask_b32_e32 v148, v147, v148, vcc
	v_sub_f32_e32 v145, v145, v146
	v_sub_f32_e32 v144, v144, v146
	v_sub_f32_e32 v143, v143, v146
	v_sub_f32_e32 v142, v142, v146
	v_sub_f32_e32 v141, v141, v146
	v_sub_f32_e32 v140, v140, v146
	v_sub_f32_e32 v139, v139, v146
	v_sub_f32_e32 v138, v138, v146
	v_pk_mul_f32 v[142:143], v[142:143], v[148:149] op_sel_hi:[1,0]
	v_pk_mul_f32 v[144:145], v[144:145], v[148:149] op_sel_hi:[1,0]
	v_pk_mul_f32 v[138:139], v[138:139], v[148:149] op_sel_hi:[1,0]
	v_pk_mul_f32 v[140:141], v[140:141], v[148:149] op_sel_hi:[1,0]
	v_lshlrev_b64 v[150:151], 11, v[192:193]
	s_waitcnt lgkmcnt(3)
	v_pk_fma_f32 v[144:145], v[144:145], v[164:165], v[198:199]
	v_pk_fma_f32 v[142:143], v[142:143], v[162:163], v[196:197]
	s_waitcnt lgkmcnt(2)
	v_pk_fma_f32 v[162:163], v[140:141], v[172:173], v[212:213]
	v_pk_fma_f32 v[164:165], v[138:139], v[170:171], v[210:211]
	v_pk_fma_f32 v[138:139], v[142:143], s[94:95], v[110:111] op_sel_hi:[1,0,1]
	v_pk_fma_f32 v[140:141], v[144:145], s[94:95], v[112:113] op_sel_hi:[1,0,1]
	v_pk_fma_f32 v[142:143], v[164:165], s[94:95], v[106:107] op_sel_hi:[1,0,1]
	v_pk_fma_f32 v[144:145], v[162:163], s[94:95], v[108:109] op_sel_hi:[1,0,1]
	s_and_b64 vcc, exec, s[12:13]
	v_lshl_add_u64 v[106:107], v[150:151], 1, s[34:35]
	s_cbranch_vccnz .LBB0_687
	v_cvt_pk_f16_f32 v108, v138, v139
	v_cvt_pk_f16_f32 v109, v140, v141
	v_cvt_pk_f16_f32 v110, v142, v143
	v_cvt_pk_f16_f32 v111, v144, v145
	v_lshl_add_u64 v[112:113], v[186:187], 1, v[106:107]
	s_mov_b64 s[62:63], 0
	global_store_dwordx4 v[112:113], v[108:111], off

; #define LAS __attribute__((address_space(3)))
;     __device__ __forceinline__ const float* resrow(int row, int colb) const { return (row < 8192 ? res0 + (size_t)row * DM : res1 + (size_t)(row - 8192) * DM) + colb; }
;     __device__ __forceinline__ void operator()(f32x4 (&acc)[2][2][4][2], const Unit& u, int wr, int wc, int fr, int fq) const {
;     ...
;                 if (ai * 4 + m < 7) { const int rown = row0 + ((ai * 4 + m + 1) >> 2) * HALF + ((ai * 4 + m + 1) & 3) * 16; const float* rp = resrow(rown, colb);
; #pragma unroll
;                     for (int bj = 0; bj < 2; ++bj) { rn[bj][0] = ldg4(rp + bj * HALF); rn[bj][1] = ldg4(rp + bj * HALF + 4); }
;                     if (hasln) stn = ldg2(pstats + 2 * (size_t)rown);
;                 }
;                 float* op = out + (size_t)row * DM + colb; h16* zp = zh + (size_t)row * DM + colb;
;                 float mu = 0.f, rs = 1.f; if (hasln) { mu = st.x * (1.0f / DM); rs = rsqrtf(fmaxf(st.y * (1.0f / DM) - mu * mu, 0.f) + LN_EPS); }
;                 float sm = 0.f, sq = 0.f;
; #pragma unroll
;                 for (int bj = 0; bj < 2; ++bj) {
;                     f32x4 r0 = r[bj][0], r1 = r[bj][1];
;                     if (hasln) { const f32x4 g0 = *(const LAS f32x4*)(slot + bj * 32 + 8 * fq), g1 = *(const LAS f32x4*)(slot + bj * 32 + 8 * fq + 4),
;                                              b0 = *(const LAS f32x4*)(slot + 64 + bj * 32 + 8 * fq), b1 = *(const LAS f32x4*)(slot + 64 + bj * 32 + 8 * fq + 4);
;                         r0 = (r0 - mu) * rs * g0 + b0; r1 = (r1 - mu) * rs * g1 + b1; }
;                     const f32x4 z0 = r0 * ALPHA + acc[ai][bj][m][0], z1 = r1 * ALPHA + acc[ai][bj][m][1];
;                     if (zf == nullptr) { stg4(op + bj * HALF, z0); stg4(op + bj * HALF + 4, z1); }
;                     else { u32x4 w; w.x = pk2(z0[0], z0[1]); w.y = pk2(z0[2], z0[3]); w.z = pk2(z1[0], z1[1]); w.w = pk2(z1[2], z1[3]); stg4h(zf + (size_t)row * DM + colb + bj * HALF, w); }
;                     sm += ((z0[0] + z0[1]) + (z0[2] + z0[3])) + ((z1[0] + z1[1]) + (z1[2] + z1[3]));
;                     sq += ((z0[0] * z0[0] + z0[1] * z0[1]) + (z0[2] * z0[2] + z0[3] * z0[3])) + ((z1[0] * z1[0] + z1[1] * z1[1]) + (z1[2] * z1[2] + z1[3] * z1[3]));
.LBB0_695:
	s_nop 1
	v_add_f32_e32 v98, v139, v138
	v_add_f32_e32 v99, v141, v140
	v_or_b32_e32 v146, 48, v184
	v_add_f32_e32 v150, v99, v98
	v_add_u32_e32 v98, 0xffffe030, v184
	v_ashrrev_i32_e32 v147, 31, v146
	v_cmp_gt_i32_e32 vcc, s55, v146
	v_mov_b32_e32 v100, s74
	v_mov_b32_e32 v101, s15
	v_cndmask_b32_e32 v99, 0, v147, vcc
	v_cndmask_b32_e32 v98, v98, v146, vcc
	v_cndmask_b32_e32 v101, v100, v101, vcc
	v_mov_b32_e32 v100, s71
	v_mov_b32_e32 v102, s14
	v_cndmask_b32_e32 v100, v100, v102, vcc
	v_lshlrev_b64 v[98:99], 13, v[98:99]
	v_lshl_add_u64 v[98:99], v[100:101], 0, v[98:99]
	v_lshl_add_u64 v[102:103], v[98:99], 0, v[188:189]
	global_load_dwordx4 v[106:109], v[102:103], off offset:16
	global_load_dwordx4 v[110:113], v[102:103], off
	global_load_dwordx4 v[98:101], v[102:103], off offset:528
	s_nop 0
	global_load_dwordx4 v[102:105], v[102:103], off offset:512
	v_lshl_add_u64 v[148:149], v[146:147], 3, s[36:37]
	global_load_dwordx2 v[148:149], v[148:149], off
	v_mul_f32_e32 v138, v138, v138
	v_fmac_f32_e32 v138, v139, v139
	v_mul_f32_e32 v139, v140, v140
	v_fmac_f32_e32 v139, v141, v141
	v_add_f32_e32 v138, v139, v138
	v_mul_f32_e32 v139, v142, v142
	v_mul_f32_e32 v140, v144, v144
	v_fmac_f32_e32 v139, v143, v143
	v_fmac_f32_e32 v140, v145, v145
	v_add_f32_e32 v139, v140, v139
	v_add_f32_e32 v138, v139, v138
	v_add_f32_e32 v139, v131, v130
	v_mul_f32_e32 v130, v130, v130
	v_add_f32_e32 v151, v143, v142
	v_add_f32_e32 v162, v145, v144
	v_add_f32_e32 v140, v132, v133
	v_fmac_f32_e32 v130, v131, v131
	v_mul_f32_e32 v131, v133, v133
	v_add_f32_e32 v151, v162, v151
	v_add_f32_e32 v139, v140, v139
	v_add_f32_e32 v140, v135, v134
	v_add_f32_e32 v141, v137, v136
	v_fmac_f32_e32 v131, v132, v132
	v_add_f32_e32 v150, v151, v150
	v_add_f32_e32 v140, v141, v140
	v_add_f32_e32 v130, v131, v130
	v_mul_f32_e32 v131, v134, v134
	v_mul_f32_e32 v132, v136, v136
	v_add_f32_e32 v150, 0, v150
	v_add_f32_e32 v139, v140, v139
	v_fmac_f32_e32 v131, v135, v135
	v_fmac_f32_e32 v132, v137, v137
	v_add_f32_e32 v139, v150, v139
	v_add_f32_e32 v131, v132, v131
	ds_bpermute_b32 v133, v156, v139
	v_add_f32_e32 v130, v131, v130
	v_add_f32_e32 v132, v138, v130
	s_waitcnt vmcnt(7)
	v_pk_mul_f32 v[130:131], v[194:195], s[54:55] op_sel_hi:[1,0]
	ds_read_b128 v[140:143], v207
	ds_read_b128 v[162:165], v207 offset:16
	ds_read_b128 v[170:173], v207 offset:256
	ds_read_b128 v[192:195], v207 offset:272
	v_fma_f32 v131, -v130, v130, v131
	v_max_f32_e32 v131, 0, v131
	v_add_f32_e32 v131, 0x3727c5ac, v131
	s_waitcnt lgkmcnt(4)
	v_add_f32_e32 v136, v139, v133
	ds_bpermute_b32 v133, v156, v132
	v_mul_f32_e32 v134, 0x4b800000, v131
	v_cmp_gt_f32_e32 vcc, s60, v131
	ds_bpermute_b32 v137, v157, v136
	v_sub_f32_e32 v129, v129, v130
	v_cndmask_b32_e32 v131, v131, v134, vcc
	v_rsq_f32_e32 v131, v131
	s_waitcnt lgkmcnt(1)
	v_add_f32_e32 v138, v132, v133
	ds_bpermute_b32 v139, v157, v138
	v_sub_f32_e32 v128, v128, v130
	v_mul_f32_e32 v132, 0x45800000, v131
	v_cndmask_b32_e32 v132, v131, v132, vcc
	v_sub_f32_e32 v127, v127, v130
	v_sub_f32_e32 v126, v126, v130
	v_sub_f32_e32 v125, v125, v130
	v_sub_f32_e32 v124, v124, v130
	v_sub_f32_e32 v123, v123, v130
	v_sub_f32_e32 v122, v122, v130
	v_pk_mul_f32 v[126:127], v[126:127], v[132:133] op_sel_hi:[1,0]
	v_pk_mul_f32 v[128:129], v[128:129], v[132:133] op_sel_hi:[1,0]
	v_pk_mul_f32 v[122:123], v[122:123], v[132:133] op_sel_hi:[1,0]
	v_pk_mul_f32 v[124:125], v[124:125], v[132:133] op_sel_hi:[1,0]
	v_lshlrev_b64 v[134:135], 11, v[190:191]
	v_pk_fma_f32 v[128:129], v[128:129], v[142:143], v[172:173]
	v_pk_fma_f32 v[126:127], v[126:127], v[140:141], v[170:171]
	v_pk_fma_f32 v[140:141], v[124:125], v[164:165], v[194:195]
	v_pk_fma_f32 v[142:143], v[122:123], v[162:163], v[192:193]
	v_pk_fma_f32 v[122:123], v[126:127], s[94:95], v[94:95] op_sel_hi:[1,0,1]
	v_pk_fma_f32 v[124:125], v[128:129], s[94:95], v[96:97] op_sel_hi:[1,0,1]
	v_pk_fma_f32 v[126:127], v[142:143], s[94:95], v[90:91] op_sel_hi:[1,0,1]
	v_pk_fma_f32 v[128:129], v[140:141], s[94:95], v[92:93] op_sel_hi:[1,0,1]
	s_mov_b64 s[62:63], -1
	s_and_b64 vcc, exec, s[12:13]
	v_lshl_add_u64 v[90:91], v[134:135], 1, s[34:35]
	s_cbranch_vccnz .LBB0_697
	v_cvt_pk_f16_f32 v92, v122, v123
	v_cvt_pk_f16_f32 v93, v124, v125
	v_cvt_pk_f16_f32 v94, v126, v127
	v_cvt_pk_f16_f32 v95, v128, v129
	v_lshl_add_u64 v[96:97], v[186:187], 1, v[90:91]
	s_mov_b64 s[62:63], 0
	global_store_dwordx4 v[96:97], v[92:95], off

; #define LAS __attribute__((address_space(3)))
;     __device__ __forceinline__ const float* resrow(int row, int colb) const { return (row < 8192 ? res0 + (size_t)row * DM : res1 + (size_t)(row - 8192) * DM) + colb; }
;     __device__ __forceinline__ void operator()(f32x4 (&acc)[2][2][4][2], const Unit& u, int wr, int wc, int fr, int fq) const {
;     ...
;                 if (ai * 4 + m < 7) { const int rown = row0 + ((ai * 4 + m + 1) >> 2) * HALF + ((ai * 4 + m + 1) & 3) * 16; const float* rp = resrow(rown, colb);
; #pragma unroll
;                     for (int bj = 0; bj < 2; ++bj) { rn[bj][0] = ldg4(rp + bj * HALF); rn[bj][1] = ldg4(rp + bj * HALF + 4); }
;                     if (hasln) stn = ldg2(pstats + 2 * (size_t)rown);
;                 }
;                 float* op = out + (size_t)row * DM + colb; h16* zp = zh + (size_t)row * DM + colb;
;                 float mu = 0.f, rs = 1.f; if (hasln) { mu = st.x * (1.0f / DM); rs = rsqrtf(fmaxf(st.y * (1.0f / DM) - mu * mu, 0.f) + LN_EPS); }
;                 float sm = 0.f, sq = 0.f;
; #pragma unroll
;                 for (int bj = 0; bj < 2; ++bj) {
;                     f32x4 r0 = r[bj][0], r1 = r[bj][1];
;                     if (hasln) { const f32x4 g0 = *(const LAS f32x4*)(slot + bj * 32 + 8 * fq), g1 = *(const LAS f32x4*)(slot + bj * 32 + 8 * fq + 4),
;                                              b0 = *(const LAS f32x4*)(slot + 64 + bj * 32 + 8 * fq), b1 = *(const LAS f32x4*)(slot + 64 + bj * 32 + 8 * fq + 4);
;                         r0 = (r0 - mu) * rs * g0 + b0; r1 = (r1 - mu) * rs * g1 + b1; }
;                     const f32x4 z0 = r0 * ALPHA + acc[ai][bj][m][0], z1 = r1 * ALPHA + acc[ai][bj][m][1];
;                     if (zf == nullptr) { stg4(op + bj * HALF, z0); stg4(op + bj * HALF + 4, z1); }
;                     else { u32x4 w; w.x = pk2(z0[0], z0[1]); w.y = pk2(z0[2], z0[3]); w.z = pk2(z1[0], z1[1]); w.w = pk2(z1[2], z1[3]); stg4h(zf + (size_t)row * DM + colb + bj * HALF, w); }
;                     sm += ((z0[0] + z0[1]) + (z0[2] + z0[3])) + ((z1[0] + z1[1]) + (z1[2] + z1[3]));
;                     sq += ((z0[0] * z0[0] + z0[1] * z0[1]) + (z0[2] * z0[2] + z0[3] * z0[3])) + ((z1[0] * z1[0] + z1[1] * z1[1]) + (z1[2] * z1[2] + z1[3] * z1[3]));
.LBB0_705:
	s_nop 1
	v_add_f32_e32 v82, v123, v122
	v_add_f32_e32 v83, v125, v124
	v_add_u32_e32 v130, 0x80, v184
	s_movk_i32 s22, 0x1f80
	v_add_f32_e32 v134, v83, v82
	v_add_u32_e32 v82, 0xffffe080, v184
	v_ashrrev_i32_e32 v131, 31, v130
	v_cmp_gt_i32_e32 vcc, s22, v184
	v_mov_b32_e32 v84, s74
	v_mov_b32_e32 v85, s15
	v_cndmask_b32_e32 v83, 0, v131, vcc
	v_cndmask_b32_e32 v82, v82, v130, vcc
	v_cndmask_b32_e32 v85, v84, v85, vcc
	v_mov_b32_e32 v84, s71
	v_mov_b32_e32 v86, s14
	v_cndmask_b32_e32 v84, v84, v86, vcc
	v_lshlrev_b64 v[82:83], 13, v[82:83]
	v_lshl_add_u64 v[82:83], v[84:85], 0, v[82:83]
	v_lshl_add_u64 v[86:87], v[82:83], 0, v[188:189]
	global_load_dwordx4 v[90:93], v[86:87], off offset:16
	global_load_dwordx4 v[94:97], v[86:87], off
	global_load_dwordx4 v[82:85], v[86:87], off offset:528
	s_nop 0
	global_load_dwordx4 v[86:89], v[86:87], off offset:512
	v_lshl_add_u64 v[132:133], v[130:131], 3, s[36:37]
	global_load_dwordx2 v[132:133], v[132:133], off
	v_mul_f32_e32 v122, v122, v122
	v_fmac_f32_e32 v122, v123, v123
	v_mul_f32_e32 v123, v124, v124
	v_fmac_f32_e32 v123, v125, v125
	v_add_f32_e32 v122, v123, v122
	v_mul_f32_e32 v123, v126, v126
	v_mul_f32_e32 v124, v128, v128
	v_fmac_f32_e32 v123, v127, v127
	v_fmac_f32_e32 v124, v129, v129
	v_add_f32_e32 v123, v124, v123
	v_add_f32_e32 v122, v123, v122
	v_add_f32_e32 v123, v115, v114
	v_mul_f32_e32 v114, v114, v114
	v_add_f32_e32 v135, v127, v126
	v_add_f32_e32 v140, v129, v128
	v_add_f32_e32 v124, v116, v117
	v_fmac_f32_e32 v114, v115, v115
	v_mul_f32_e32 v115, v117, v117
	v_add_f32_e32 v135, v140, v135
	v_add_f32_e32 v123, v124, v123
	v_add_f32_e32 v124, v119, v118
	v_add_f32_e32 v125, v121, v120
	v_fmac_f32_e32 v115, v116, v116
	v_add_f32_e32 v134, v135, v134
	v_add_f32_e32 v124, v125, v124
	v_add_f32_e32 v114, v115, v114
	v_mul_f32_e32 v115, v118, v118
	v_mul_f32_e32 v116, v120, v120
	v_add_f32_e32 v134, 0, v134
	v_add_f32_e32 v123, v124, v123
	v_fmac_f32_e32 v115, v119, v119
	v_fmac_f32_e32 v116, v121, v121
	v_add_f32_e32 v123, v134, v123
	v_add_f32_e32 v115, v116, v115
	ds_bpermute_b32 v117, v156, v123
	v_add_f32_e32 v114, v115, v114
	v_add_f32_e32 v116, v122, v114
	s_waitcnt vmcnt(7)
	v_pk_mul_f32 v[114:115], v[148:149], s[54:55] op_sel_hi:[1,0]
	ds_read_b128 v[124:127], v207
	ds_read_b128 v[140:143], v207 offset:16
	ds_read_b128 v[148:151], v207 offset:256
	ds_read_b128 v[162:165], v207 offset:272
	v_fma_f32 v115, -v114, v114, v115
	v_max_f32_e32 v115, 0, v115
	v_add_f32_e32 v115, 0x3727c5ac, v115
	s_waitcnt lgkmcnt(4)
	v_add_f32_e32 v120, v123, v117
	ds_bpermute_b32 v117, v156, v116
	v_mul_f32_e32 v118, 0x4b800000, v115
	v_cmp_gt_f32_e32 vcc, s60, v115
	ds_bpermute_b32 v121, v157, v120
	v_sub_f32_e32 v113, v113, v114
	v_cndmask_b32_e32 v115, v115, v118, vcc
	v_rsq_f32_e32 v115, v115
	s_waitcnt lgkmcnt(1)
	v_add_f32_e32 v122, v116, v117
	ds_bpermute_b32 v123, v157, v122
	v_sub_f32_e32 v112, v112, v114
	v_mul_f32_e32 v116, 0x45800000, v115
	v_cndmask_b32_e32 v116, v115, v116, vcc
	v_sub_f32_e32 v111, v111, v114
	v_sub_f32_e32 v110, v110, v114
	v_sub_f32_e32 v109, v109, v114
	v_sub_f32_e32 v108, v108, v114
	v_sub_f32_e32 v107, v107, v114
	v_sub_f32_e32 v106, v106, v114
	v_pk_mul_f32 v[110:111], v[110:111], v[116:117] op_sel_hi:[1,0]
	v_pk_mul_f32 v[112:113], v[112:113], v[116:117] op_sel_hi:[1,0]
	v_pk_mul_f32 v[106:107], v[106:107], v[116:117] op_sel_hi:[1,0]
	v_pk_mul_f32 v[108:109], v[108:109], v[116:117] op_sel_hi:[1,0]
	v_lshlrev_b64 v[118:119], 11, v[146:147]
	v_pk_fma_f32 v[112:113], v[112:113], v[126:127], v[150:151]
	v_pk_fma_f32 v[110:111], v[110:111], v[124:125], v[148:149]
	v_pk_fma_f32 v[124:125], v[108:109], v[142:143], v[164:165]
	v_pk_fma_f32 v[126:127], v[106:107], v[140:141], v[162:163]
	v_pk_fma_f32 v[106:107], v[110:111], s[94:95], v[78:79] op_sel_hi:[1,0,1]
	v_pk_fma_f32 v[108:109], v[112:113], s[94:95], v[80:81] op_sel_hi:[1,0,1]
	v_pk_fma_f32 v[110:111], v[126:127], s[94:95], v[74:75] op_sel_hi:[1,0,1]
	v_pk_fma_f32 v[112:113], v[124:125], s[94:95], v[76:77] op_sel_hi:[1,0,1]
	s_mov_b64 s[62:63], -1
	s_and_b64 vcc, exec, s[12:13]
	v_lshl_add_u64 v[74:75], v[118:119], 1, s[34:35]
	s_cbranch_vccnz .LBB0_707
	v_cvt_pk_f16_f32 v76, v106, v107
	v_cvt_pk_f16_f32 v77, v108, v109
	v_cvt_pk_f16_f32 v78, v110, v111
	v_cvt_pk_f16_f32 v79, v112, v113
	v_lshl_add_u64 v[80:81], v[186:187], 1, v[74:75]
	s_mov_b64 s[62:63], 0
	global_store_dwordx4 v[80:81], v[76:79], off

; #define LAS __attribute__((address_space(3)))
;     __device__ __forceinline__ const float* resrow(int row, int colb) const { return (row < 8192 ? res0 + (size_t)row * DM : res1 + (size_t)(row - 8192) * DM) + colb; }
;     __device__ __forceinline__ void operator()(f32x4 (&acc)[2][2][4][2], const Unit& u, int wr, int wc, int fr, int fq) const {
;     ...
;                 if (ai * 4 + m < 7) { const int rown = row0 + ((ai * 4 + m + 1) >> 2) * HALF + ((ai * 4 + m + 1) & 3) * 16; const float* rp = resrow(rown, colb);
; #pragma unroll
;                     for (int bj = 0; bj < 2; ++bj) { rn[bj][0] = ldg4(rp + bj * HALF); rn[bj][1] = ldg4(rp + bj * HALF + 4); }
;                     if (hasln) stn = ldg2(pstats + 2 * (size_t)rown);
;                 }
;                 float* op = out + (size_t)row * DM + colb; h16* zp = zh + (size_t)row * DM + colb;
;                 float mu = 0.f, rs = 1.f; if (hasln) { mu = st.x * (1.0f / DM); rs = rsqrtf(fmaxf(st.y * (1.0f / DM) - mu * mu, 0.f) + LN_EPS); }
;                 float sm = 0.f, sq = 0.f;
; #pragma unroll
;                 for (int bj = 0; bj < 2; ++bj) {
;                     f32x4 r0 = r[bj][0], r1 = r[bj][1];
;                     if (hasln) { const f32x4 g0 = *(const LAS f32x4*)(slot + bj * 32 + 8 * fq), g1 = *(const LAS f32x4*)(slot + bj * 32 + 8 * fq + 4),
;                                              b0 = *(const LAS f32x4*)(slot + 64 + bj * 32 + 8 * fq), b1 = *(const LAS f32x4*)(slot + 64 + bj * 32 + 8 * fq + 4);
;                         r0 = (r0 - mu) * rs * g0 + b0; r1 = (r1 - mu) * rs * g1 + b1; }
;                     const f32x4 z0 = r0 * ALPHA + acc[ai][bj][m][0], z1 = r1 * ALPHA + acc[ai][bj][m][1];
;                     if (zf == nullptr) { stg4(op + bj * HALF, z0); stg4(op + bj * HALF + 4, z1); }
;                     else { u32x4 w; w.x = pk2(z0[0], z0[1]); w.y = pk2(z0[2], z0[3]); w.z = pk2(z1[0], z1[1]); w.w = pk2(z1[2], z1[3]); stg4h(zf + (size_t)row * DM + colb + bj * HALF, w); }
;                     sm += ((z0[0] + z0[1]) + (z0[2] + z0[3])) + ((z1[0] + z1[1]) + (z1[2] + z1[3]));
;                     sq += ((z0[0] * z0[0] + z0[1] * z0[1]) + (z0[2] * z0[2] + z0[3] * z0[3])) + ((z1[0] * z1[0] + z1[1] * z1[1]) + (z1[2] * z1[2] + z1[3] * z1[3]));
.LBB0_715:
	s_nop 1
	v_add_f32_e32 v66, v107, v106
	v_add_f32_e32 v67, v109, v108
	v_or_b32_e32 v114, 16, v130
	v_add_f32_e32 v116, v67, v66
	v_add_u32_e32 v66, 0xffffe090, v184
	v_ashrrev_i32_e32 v115, 31, v114
	v_cmp_gt_i32_e32 vcc, s55, v114
	v_mov_b32_e32 v68, s74
	v_mov_b32_e32 v69, s15
	v_cndmask_b32_e32 v67, 0, v115, vcc
	v_cndmask_b32_e32 v66, v66, v114, vcc
	v_cndmask_b32_e32 v69, v68, v69, vcc
	v_mov_b32_e32 v68, s71
	v_mov_b32_e32 v70, s14
	v_cndmask_b32_e32 v68, v68, v70, vcc
	v_lshlrev_b64 v[66:67], 13, v[66:67]
	v_lshl_add_u64 v[66:67], v[68:69], 0, v[66:67]
	v_lshl_add_u64 v[70:71], v[66:67], 0, v[188:189]
	global_load_dwordx4 v[74:77], v[70:71], off offset:16
	global_load_dwordx4 v[78:81], v[70:71], off
	global_load_dwordx4 v[66:69], v[70:71], off offset:528
	s_nop 0
	global_load_dwordx4 v[70:73], v[70:71], off offset:512
	v_lshl_add_u64 v[114:115], v[114:115], 3, s[36:37]
	global_load_dwordx2 v[114:115], v[114:115], off
	v_mul_f32_e32 v106, v106, v106
	v_fmac_f32_e32 v106, v107, v107
	v_mul_f32_e32 v107, v108, v108
	v_fmac_f32_e32 v107, v109, v109
	v_add_f32_e32 v106, v107, v106
	v_mul_f32_e32 v107, v110, v110
	v_mul_f32_e32 v108, v112, v112
	v_fmac_f32_e32 v107, v111, v111
	v_fmac_f32_e32 v108, v113, v113
	v_add_f32_e32 v107, v108, v107
	v_add_f32_e32 v106, v107, v106
	v_add_f32_e32 v107, v99, v98
	v_mul_f32_e32 v98, v98, v98
	v_add_f32_e32 v117, v111, v110
	v_add_f32_e32 v118, v113, v112
	v_add_f32_e32 v108, v100, v101
	v_fmac_f32_e32 v98, v99, v99
	v_mul_f32_e32 v99, v101, v101
	v_add_f32_e32 v117, v118, v117
	v_add_f32_e32 v107, v108, v107
	v_add_f32_e32 v108, v103, v102
	v_add_f32_e32 v109, v105, v104
	v_fmac_f32_e32 v99, v100, v100
	v_add_f32_e32 v116, v117, v116
	v_add_f32_e32 v108, v109, v108
	v_add_f32_e32 v98, v99, v98
	v_mul_f32_e32 v99, v102, v102
	v_mul_f32_e32 v100, v104, v104
	v_add_f32_e32 v116, 0, v116
	v_add_f32_e32 v107, v108, v107
	v_fmac_f32_e32 v99, v103, v103
	v_fmac_f32_e32 v100, v105, v105
	v_add_f32_e32 v107, v116, v107
	v_add_f32_e32 v99, v100, v99
	ds_bpermute_b32 v101, v156, v107
	v_add_f32_e32 v98, v99, v98
	v_add_f32_e32 v100, v106, v98
	s_waitcnt vmcnt(7)
	v_pk_mul_f32 v[98:99], v[132:133], s[54:55] op_sel_hi:[1,0]
	ds_read_b128 v[108:111], v207
	ds_read_b128 v[116:119], v207 offset:16
	ds_read_b128 v[124:127], v207 offset:256
	ds_read_b128 v[132:135], v207 offset:272
	v_fma_f32 v99, -v98, v98, v99
	v_max_f32_e32 v99, 0, v99
	v_add_f32_e32 v99, 0x3727c5ac, v99
	s_waitcnt lgkmcnt(4)
	v_add_f32_e32 v104, v107, v101
	ds_bpermute_b32 v101, v156, v100
	v_mul_f32_e32 v102, 0x4b800000, v99
	v_cmp_gt_f32_e32 vcc, s60, v99
	ds_bpermute_b32 v105, v157, v104
	v_sub_f32_e32 v97, v97, v98
	v_cndmask_b32_e32 v99, v99, v102, vcc
	v_rsq_f32_e32 v99, v99
	s_waitcnt lgkmcnt(1)
	v_add_f32_e32 v106, v100, v101
	ds_bpermute_b32 v107, v157, v106
	v_sub_f32_e32 v96, v96, v98
	v_mul_f32_e32 v100, 0x45800000, v99
	v_cndmask_b32_e32 v100, v99, v100, vcc
	v_sub_f32_e32 v95, v95, v98
	v_sub_f32_e32 v94, v94, v98
	v_sub_f32_e32 v93, v93, v98
	v_sub_f32_e32 v92, v92, v98
	v_sub_f32_e32 v91, v91, v98
	v_sub_f32_e32 v90, v90, v98
	v_pk_mul_f32 v[94:95], v[94:95], v[100:101] op_sel_hi:[1,0]
	v_pk_mul_f32 v[96:97], v[96:97], v[100:101] op_sel_hi:[1,0]
	v_pk_mul_f32 v[90:91], v[90:91], v[100:101] op_sel_hi:[1,0]
	v_pk_mul_f32 v[92:93], v[92:93], v[100:101] op_sel_hi:[1,0]
	v_lshlrev_b64 v[102:103], 11, v[130:131]
	v_pk_fma_f32 v[96:97], v[96:97], v[110:111], v[126:127]
	v_pk_fma_f32 v[94:95], v[94:95], v[108:109], v[124:125]
	v_pk_fma_f32 v[108:109], v[92:93], v[118:119], v[134:135]
	v_pk_fma_f32 v[110:111], v[90:91], v[116:117], v[132:133]
	v_pk_fma_f32 v[90:91], v[94:95], s[94:95], v[62:63] op_sel_hi:[1,0,1]
	v_pk_fma_f32 v[92:93], v[96:97], s[94:95], v[64:65] op_sel_hi:[1,0,1]
	v_pk_fma_f32 v[94:95], v[110:111], s[94:95], v[58:59] op_sel_hi:[1,0,1]
	v_pk_fma_f32 v[96:97], v[108:109], s[94:95], v[60:61] op_sel_hi:[1,0,1]
	s_mov_b64 s[62:63], -1
	s_and_b64 vcc, exec, s[12:13]
	v_lshl_add_u64 v[58:59], v[102:103], 1, s[34:35]
	s_cbranch_vccnz .LBB0_717
	v_cvt_pk_f16_f32 v60, v90, v91
	v_cvt_pk_f16_f32 v61, v92, v93
	v_cvt_pk_f16_f32 v62, v94, v95
	v_cvt_pk_f16_f32 v63, v96, v97
	v_lshl_add_u64 v[64:65], v[186:187], 1, v[58:59]
	s_mov_b64 s[62:63], 0
	global_store_dwordx4 v[64:65], v[60:63], off

; #define LAS __attribute__((address_space(3)))
;     __device__ __forceinline__ const float* resrow(int row, int colb) const { return (row < 8192 ? res0 + (size_t)row * DM : res1 + (size_t)(row - 8192) * DM) + colb; }
;     __device__ __forceinline__ void operator()(f32x4 (&acc)[2][2][4][2], const Unit& u, int wr, int wc, int fr, int fq) const {
;     ...
;                 if (ai * 4 + m < 7) { const int rown = row0 + ((ai * 4 + m + 1) >> 2) * HALF + ((ai * 4 + m + 1) & 3) * 16; const float* rp = resrow(rown, colb);
; #pragma unroll
;                     for (int bj = 0; bj < 2; ++bj) { rn[bj][0] = ldg4(rp + bj * HALF); rn[bj][1] = ldg4(rp + bj * HALF + 4); }
;                     if (hasln) stn = ldg2(pstats + 2 * (size_t)rown);
;                 }
;                 float* op = out + (size_t)row * DM + colb; h16* zp = zh + (size_t)row * DM + colb;
;                 float mu = 0.f, rs = 1.f; if (hasln) { mu = st.x * (1.0f / DM); rs = rsqrtf(fmaxf(st.y * (1.0f / DM) - mu * mu, 0.f) + LN_EPS); }
;                 float sm = 0.f, sq = 0.f;
; #pragma unroll
;                 for (int bj = 0; bj < 2; ++bj) {
;                     f32x4 r0 = r[bj][0], r1 = r[bj][1];
;                     if (hasln) { const f32x4 g0 = *(const LAS f32x4*)(slot + bj * 32 + 8 * fq), g1 = *(const LAS f32x4*)(slot + bj * 32 + 8 * fq + 4),
;                                              b0 = *(const LAS f32x4*)(slot + 64 + bj * 32 + 8 * fq), b1 = *(const LAS f32x4*)(slot + 64 + bj * 32 + 8 * fq + 4);
;                         r0 = (r0 - mu) * rs * g0 + b0; r1 = (r1 - mu) * rs * g1 + b1; }
;                     const f32x4 z0 = r0 * ALPHA + acc[ai][bj][m][0], z1 = r1 * ALPHA + acc[ai][bj][m][1];
;                     if (zf == nullptr) { stg4(op + bj * HALF, z0); stg4(op + bj * HALF + 4, z1); }
;                     else { u32x4 w; w.x = pk2(z0[0], z0[1]); w.y = pk2(z0[2], z0[3]); w.z = pk2(z1[0], z1[1]); w.w = pk2(z1[2], z1[3]); stg4h(zf + (size_t)row * DM + colb + bj * HALF, w); }
;                     sm += ((z0[0] + z0[1]) + (z0[2] + z0[3])) + ((z1[0] + z1[1]) + (z1[2] + z1[3]));
;                     sq += ((z0[0] * z0[0] + z0[1] * z0[1]) + (z0[2] * z0[2] + z0[3] * z0[3])) + ((z1[0] * z1[0] + z1[1] * z1[1]) + (z1[2] * z1[2] + z1[3] * z1[3]));
.LBB0_725:
	s_nop 1
	v_add_f32_e32 v50, v91, v90
	v_add_f32_e32 v51, v93, v92
	v_add_f32_e32 v50, v51, v50
	v_add_f32_e32 v51, v95, v94
	v_add_f32_e32 v52, v97, v96
	v_add_f32_e32 v51, v52, v51
	v_add_f32_e32 v50, v51, v50
	v_or_b32_e32 v98, 32, v130
	v_add_f32_e32 v100, 0, v50
	v_add_u32_e32 v50, 0xffffe0a0, v184
	v_ashrrev_i32_e32 v99, 31, v98
	v_cmp_gt_i32_e32 vcc, s55, v98
	v_mov_b32_e32 v52, s74
	v_mov_b32_e32 v53, s15
	v_cndmask_b32_e32 v51, 0, v99, vcc
	v_cndmask_b32_e32 v50, v50, v98, vcc
	v_cndmask_b32_e32 v53, v52, v53, vcc
	v_mov_b32_e32 v52, s71
	v_mov_b32_e32 v54, s14
	v_cndmask_b32_e32 v52, v52, v54, vcc
	v_lshlrev_b64 v[50:51], 13, v[50:51]
	v_lshl_add_u64 v[50:51], v[52:53], 0, v[50:51]
	v_lshl_add_u64 v[54:55], v[50:51], 0, v[188:189]
	global_load_dwordx4 v[58:61], v[54:55], off offset:16
	global_load_dwordx4 v[62:65], v[54:55], off
	global_load_dwordx4 v[50:53], v[54:55], off offset:528
	s_nop 0
	global_load_dwordx4 v[54:57], v[54:55], off offset:512
	v_lshl_add_u64 v[98:99], v[98:99], 3, s[36:37]
	global_load_dwordx2 v[98:99], v[98:99], off
	v_mul_f32_e32 v90, v90, v90
	v_fmac_f32_e32 v90, v91, v91
	v_mul_f32_e32 v91, v92, v92
	v_fmac_f32_e32 v91, v93, v93
	v_add_f32_e32 v90, v91, v90
	v_mul_f32_e32 v91, v94, v94
	v_mul_f32_e32 v92, v96, v96
	v_fmac_f32_e32 v91, v95, v95
	v_fmac_f32_e32 v92, v97, v97
	v_add_f32_e32 v91, v92, v91
	v_add_f32_e32 v90, v91, v90
	v_add_f32_e32 v91, v83, v82
	v_mul_f32_e32 v82, v82, v82
	v_fmac_f32_e32 v82, v83, v83
	v_mul_f32_e32 v83, v85, v85
	v_fmac_f32_e32 v83, v84, v84
	v_add_f32_e32 v92, v84, v85
	v_add_f32_e32 v82, v83, v82
	v_mul_f32_e32 v83, v86, v86
	v_mul_f32_e32 v84, v88, v88
	v_add_f32_e32 v91, v92, v91
	v_add_f32_e32 v92, v87, v86
	v_add_f32_e32 v93, v89, v88
	v_fmac_f32_e32 v83, v87, v87
	v_fmac_f32_e32 v84, v89, v89
	v_add_f32_e32 v92, v93, v92
	v_add_f32_e32 v83, v84, v83
	v_add_f32_e32 v91, v92, v91
	v_add_f32_e32 v82, v83, v82
	v_add_f32_e32 v91, v100, v91
	v_add_f32_e32 v82, v90, v82
	ds_bpermute_b32 v83, v156, v91
	ds_bpermute_b32 v84, v156, v82
	v_add_u32_e32 v88, 0x90, v184
	v_ashrrev_i32_e32 v89, 31, v88
	v_lshlrev_b64 v[86:87], 11, v[88:89]
	s_waitcnt lgkmcnt(1)
	v_add_f32_e32 v90, v91, v83
	s_waitcnt lgkmcnt(0)
	v_add_f32_e32 v92, v82, v84
	s_waitcnt vmcnt(7)
	v_pk_mul_f32 v[82:83], v[114:115], s[54:55] op_sel_hi:[1,0]
	ds_read_b128 v[94:97], v207
	ds_read_b128 v[100:103], v207 offset:16
	ds_read_b128 v[108:111], v207 offset:256
	ds_read_b128 v[112:115], v207 offset:272
	v_fma_f32 v83, -v82, v82, v83
	v_max_f32_e32 v83, 0, v83
	v_add_f32_e32 v83, 0x3727c5ac, v83
	v_mul_f32_e32 v84, 0x4b800000, v83
	v_cmp_gt_f32_e32 vcc, s60, v83
	ds_bpermute_b32 v91, v157, v90
	ds_bpermute_b32 v93, v157, v92
	v_cndmask_b32_e32 v83, v83, v84, vcc
	v_rsq_f32_e32 v83, v83
	v_sub_f32_e32 v81, v81, v82
	v_sub_f32_e32 v80, v80, v82
	v_sub_f32_e32 v79, v79, v82
	v_mul_f32_e32 v84, 0x45800000, v83
	v_cndmask_b32_e32 v84, v83, v84, vcc
	v_sub_f32_e32 v78, v78, v82
	v_sub_f32_e32 v77, v77, v82
	v_sub_f32_e32 v76, v76, v82
	v_sub_f32_e32 v75, v75, v82
	v_sub_f32_e32 v74, v74, v82
	v_pk_mul_f32 v[78:79], v[78:79], v[84:85] op_sel_hi:[1,0]
	v_pk_mul_f32 v[80:81], v[80:81], v[84:85] op_sel_hi:[1,0]
	v_pk_mul_f32 v[74:75], v[74:75], v[84:85] op_sel_hi:[1,0]
	v_pk_mul_f32 v[76:77], v[76:77], v[84:85] op_sel_hi:[1,0]
	s_waitcnt lgkmcnt(3)
	v_pk_fma_f32 v[80:81], v[80:81], v[96:97], v[110:111]
	v_pk_fma_f32 v[78:79], v[78:79], v[94:95], v[108:109]
	s_waitcnt lgkmcnt(2)
	v_pk_fma_f32 v[94:95], v[76:77], v[102:103], v[114:115]
	v_pk_fma_f32 v[96:97], v[74:75], v[100:101], v[112:113]
	v_pk_fma_f32 v[74:75], v[78:79], s[94:95], v[46:47] op_sel_hi:[1,0,1]
	v_pk_fma_f32 v[76:77], v[80:81], s[94:95], v[48:49] op_sel_hi:[1,0,1]
	v_pk_fma_f32 v[78:79], v[96:97], s[94:95], v[42:43] op_sel_hi:[1,0,1]
	v_pk_fma_f32 v[80:81], v[94:95], s[94:95], v[44:45] op_sel_hi:[1,0,1]
	s_mov_b64 s[62:63], -1
	s_and_b64 vcc, exec, s[12:13]
	v_lshl_add_u64 v[42:43], v[86:87], 1, s[34:35]
	s_cbranch_vccnz .LBB0_727
	v_cvt_pk_f16_f32 v44, v74, v75
	v_cvt_pk_f16_f32 v45, v76, v77
	v_cvt_pk_f16_f32 v46, v78, v79
	v_cvt_pk_f16_f32 v47, v80, v81
	v_lshl_add_u64 v[48:49], v[186:187], 1, v[42:43]
	s_mov_b64 s[62:63], 0
	global_store_dwordx4 v[48:49], v[44:47], off

; #define LAS __attribute__((address_space(3)))
;     __device__ __forceinline__ const float* resrow(int row, int colb) const { return (row < 8192 ? res0 + (size_t)row * DM : res1 + (size_t)(row - 8192) * DM) + colb; }
;     __device__ __forceinline__ void operator()(f32x4 (&acc)[2][2][4][2], const Unit& u, int wr, int wc, int fr, int fq) const {
;     ...
;                 if (ai * 4 + m < 7) { const int rown = row0 + ((ai * 4 + m + 1) >> 2) * HALF + ((ai * 4 + m + 1) & 3) * 16; const float* rp = resrow(rown, colb);
; #pragma unroll
;                     for (int bj = 0; bj < 2; ++bj) { rn[bj][0] = ldg4(rp + bj * HALF); rn[bj][1] = ldg4(rp + bj * HALF + 4); }
;                     if (hasln) stn = ldg2(pstats + 2 * (size_t)rown);
;                 }
;                 float* op = out + (size_t)row * DM + colb; h16* zp = zh + (size_t)row * DM + colb;
;                 float mu = 0.f, rs = 1.f; if (hasln) { mu = st.x * (1.0f / DM); rs = rsqrtf(fmaxf(st.y * (1.0f / DM) - mu * mu, 0.f) + LN_EPS); }
;                 float sm = 0.f, sq = 0.f;
; #pragma unroll
;                 for (int bj = 0; bj < 2; ++bj) {
;                     f32x4 r0 = r[bj][0], r1 = r[bj][1];
;                     if (hasln) { const f32x4 g0 = *(const LAS f32x4*)(slot + bj * 32 + 8 * fq), g1 = *(const LAS f32x4*)(slot + bj * 32 + 8 * fq + 4),
;                                              b0 = *(const LAS f32x4*)(slot + 64 + bj * 32 + 8 * fq), b1 = *(const LAS f32x4*)(slot + 64 + bj * 32 + 8 * fq + 4);
;                         r0 = (r0 - mu) * rs * g0 + b0; r1 = (r1 - mu) * rs * g1 + b1; }
;                     const f32x4 z0 = r0 * ALPHA + acc[ai][bj][m][0], z1 = r1 * ALPHA + acc[ai][bj][m][1];
;                     if (zf == nullptr) { stg4(op + bj * HALF, z0); stg4(op + bj * HALF + 4, z1); }
;                     else { u32x4 w; w.x = pk2(z0[0], z0[1]); w.y = pk2(z0[2], z0[3]); w.z = pk2(z1[0], z1[1]); w.w = pk2(z1[2], z1[3]); stg4h(zf + (size_t)row * DM + colb + bj * HALF, w); }
;                     sm += ((z0[0] + z0[1]) + (z0[2] + z0[3])) + ((z1[0] + z1[1]) + (z1[2] + z1[3]));
;                     sq += ((z0[0] * z0[0] + z0[1] * z0[1]) + (z0[2] * z0[2] + z0[3] * z0[3])) + ((z1[0] * z1[0] + z1[1] * z1[1]) + (z1[2] * z1[2] + z1[3] * z1[3]));
.LBB0_735:
	s_nop 1
	v_add_f32_e32 v34, v75, v74
	v_add_f32_e32 v35, v77, v76
	v_add_f32_e32 v34, v35, v34
	v_add_f32_e32 v35, v79, v78
	v_add_f32_e32 v36, v81, v80
	v_add_f32_e32 v35, v36, v35
	v_add_f32_e32 v34, v35, v34
	v_or_b32_e32 v82, 48, v130
	v_add_f32_e32 v84, 0, v34
	v_add_u32_e32 v34, 0xffffe0b0, v184
	v_ashrrev_i32_e32 v83, 31, v82
	v_cmp_gt_i32_e32 vcc, s55, v82
	v_mov_b32_e32 v36, s74
	v_mov_b32_e32 v37, s15
	v_cndmask_b32_e32 v35, 0, v83, vcc
	v_cndmask_b32_e32 v34, v34, v82, vcc
	v_cndmask_b32_e32 v37, v36, v37, vcc
	v_mov_b32_e32 v36, s71
	v_mov_b32_e32 v38, s14
	v_cndmask_b32_e32 v36, v36, v38, vcc
	v_lshlrev_b64 v[34:35], 13, v[34:35]
	v_lshl_add_u64 v[34:35], v[36:37], 0, v[34:35]
	v_lshl_add_u64 v[38:39], v[34:35], 0, v[188:189]
	global_load_dwordx4 v[42:45], v[38:39], off offset:16
	global_load_dwordx4 v[46:49], v[38:39], off
	global_load_dwordx4 v[34:37], v[38:39], off offset:528
	s_nop 0
	global_load_dwordx4 v[38:41], v[38:39], off offset:512
	v_lshl_add_u64 v[82:83], v[82:83], 3, s[36:37]
	global_load_dwordx2 v[82:83], v[82:83], off
	v_mul_f32_e32 v74, v74, v74
	v_fmac_f32_e32 v74, v75, v75
	v_mul_f32_e32 v75, v76, v76
	v_fmac_f32_e32 v75, v77, v77
	v_add_f32_e32 v74, v75, v74
	v_mul_f32_e32 v75, v78, v78
	v_mul_f32_e32 v76, v80, v80
	v_fmac_f32_e32 v75, v79, v79
	v_fmac_f32_e32 v76, v81, v81
	v_add_f32_e32 v75, v76, v75
	v_add_f32_e32 v74, v75, v74
	v_add_f32_e32 v75, v67, v66
	v_mul_f32_e32 v66, v66, v66
	v_fmac_f32_e32 v66, v67, v67
	v_mul_f32_e32 v67, v69, v69
	v_fmac_f32_e32 v67, v68, v68
	v_add_f32_e32 v76, v68, v69
	v_add_f32_e32 v66, v67, v66
	v_mul_f32_e32 v67, v70, v70
	v_mul_f32_e32 v68, v72, v72
	v_add_f32_e32 v75, v76, v75
	v_add_f32_e32 v76, v71, v70
	v_add_f32_e32 v77, v73, v72
	v_fmac_f32_e32 v67, v71, v71
	v_fmac_f32_e32 v68, v73, v73
	v_add_f32_e32 v76, v77, v76
	v_add_f32_e32 v67, v68, v67
	v_add_f32_e32 v75, v76, v75
	v_add_f32_e32 v66, v67, v66
	v_add_f32_e32 v75, v84, v75
	v_add_f32_e32 v66, v74, v66
	ds_bpermute_b32 v67, v156, v75
	ds_bpermute_b32 v68, v156, v66
	v_add_u32_e32 v72, 0xa0, v184
	v_ashrrev_i32_e32 v73, 31, v72
	v_lshlrev_b64 v[70:71], 11, v[72:73]
	s_waitcnt lgkmcnt(1)
	v_add_f32_e32 v74, v75, v67
	s_waitcnt lgkmcnt(0)
	v_add_f32_e32 v76, v66, v68
	s_waitcnt vmcnt(7)
	v_pk_mul_f32 v[66:67], v[98:99], s[54:55] op_sel_hi:[1,0]
	ds_read_b128 v[78:81], v207
	ds_read_b128 v[84:87], v207 offset:16
	ds_read_b128 v[94:97], v207 offset:256
	ds_read_b128 v[98:101], v207 offset:272
	v_fma_f32 v67, -v66, v66, v67
	v_max_f32_e32 v67, 0, v67
	v_add_f32_e32 v67, 0x3727c5ac, v67
	v_mul_f32_e32 v68, 0x4b800000, v67
	v_cmp_gt_f32_e32 vcc, s60, v67
	ds_bpermute_b32 v75, v157, v74
	ds_bpermute_b32 v77, v157, v76
	v_cndmask_b32_e32 v67, v67, v68, vcc
	v_rsq_f32_e32 v67, v67
	v_sub_f32_e32 v65, v65, v66
	v_sub_f32_e32 v64, v64, v66
	v_sub_f32_e32 v63, v63, v66
	v_mul_f32_e32 v68, 0x45800000, v67
	v_cndmask_b32_e32 v68, v67, v68, vcc
	v_sub_f32_e32 v62, v62, v66
	v_sub_f32_e32 v61, v61, v66
	v_sub_f32_e32 v60, v60, v66
	v_sub_f32_e32 v59, v59, v66
	v_sub_f32_e32 v58, v58, v66
	v_pk_mul_f32 v[62:63], v[62:63], v[68:69] op_sel_hi:[1,0]
	v_pk_mul_f32 v[64:65], v[64:65], v[68:69] op_sel_hi:[1,0]
	v_pk_mul_f32 v[58:59], v[58:59], v[68:69] op_sel_hi:[1,0]
	v_pk_mul_f32 v[60:61], v[60:61], v[68:69] op_sel_hi:[1,0]
	s_waitcnt lgkmcnt(3)
	v_pk_fma_f32 v[64:65], v[64:65], v[80:81], v[96:97]
	v_pk_fma_f32 v[62:63], v[62:63], v[78:79], v[94:95]
	s_waitcnt lgkmcnt(2)
	v_pk_fma_f32 v[60:61], v[60:61], v[86:87], v[100:101]
	v_pk_fma_f32 v[58:59], v[58:59], v[84:85], v[98:99]
	v_pk_fma_f32 v[30:31], v[62:63], s[94:95], v[30:31] op_sel_hi:[1,0,1]
	v_pk_fma_f32 v[32:33], v[64:65], s[94:95], v[32:33] op_sel_hi:[1,0,1]
	v_pk_fma_f32 v[26:27], v[58:59], s[94:95], v[26:27] op_sel_hi:[1,0,1]
	v_pk_fma_f32 v[28:29], v[60:61], s[94:95], v[28:29] op_sel_hi:[1,0,1]
	s_mov_b64 s[62:63], -1
	s_and_b64 vcc, exec, s[12:13]
	v_lshl_add_u64 v[58:59], v[70:71], 1, s[34:35]
	s_cbranch_vccnz .LBB0_737
	v_cvt_pk_f16_f32 v60, v30, v31
	v_cvt_pk_f16_f32 v61, v32, v33
	v_cvt_pk_f16_f32 v62, v26, v27
	v_cvt_pk_f16_f32 v63, v28, v29
	v_lshl_add_u64 v[64:65], v[186:187], 1, v[58:59]
	s_mov_b64 s[62:63], 0
	global_store_dwordx4 v[64:65], v[60:63], off
